# elem phase remapped M-tile-local (each sibling group handles its own 256 tokens) so the elem->proj barrier is a sibling-group barrier too; stagger moved in front of elem
# baseline (speedup 1.0000x reference)
.LBB0_501:
	s_or_b64 exec, exec, s[0:1]
	v_mov_b32_e32 v0, v154
	s_waitcnt lgkmcnt(0)
	s_barrier
	v_readlane_b32 s8, v253, 0
	s_bitcmp1_b32 s8, 3
	s_cbranch_scc0 .Lstag_skip
	s_sleep 127
	s_sleep 127
	s_sleep 127
	s_sleep 127
.Lstag_skip:
	v_readlane_b32 s0, v253, 0
	v_and_b32_e32 v4, 0xff, v0
	v_mov_b32_e32 v0, v154
	s_lshl_b32 s0, s0, 1
	v_readfirstlane_b32 s1, v0
	s_ashr_i32 s1, s1, 8
	s_add_i32 s0, s1, s0
	s_ashr_i32 s1, s0, 31
	v_readlane_b32 s36, v253, 0
	s_and_b32 s37, s36, 7
	s_lshl_b32 s37, s37, 3
	s_bfe_u32 s38, s36, 0x30003
	s_or_b32 s37, s37, s38
	s_lshr_b32 s38, s36, 6
	s_lshl_b32 s38, s38, 1
	s_and_b32 s39, s0, 1
	s_or_b32 s38, s38, s39
	s_lshl_b32 s0, s37, 5
	s_or_b32 s0, s0, s38
	s_mov_b32 s1, 0
	s_lshl_b32 s92, s37, 13
	s_add_u32 s92, s92, 0x1fff
	s_mov_b32 s93, 0
	s_lshl_b64 s[4:5], s[0:1], 8
	v_mov_b64_e32 v[0:1], 0x7ffff
	v_cmp_gt_u64_e32 vcc, s[4:5], v[0:1]
	s_cbranch_vccnz .LBB0_505
	s_lshl_b64 s[0:1], s[0:1], 11
	v_readlane_b32 s6, v254, 7
	v_readlane_b32 s8, v254, 9
	s_movk_i32 s10, 0x800
	v_readlane_b32 s12, v254, 40
	s_movk_i32 s26, 0x4000
	v_mov_b32_e32 v1, s5
	v_or_b32_e32 v0, s4, v4
	v_lshl_or_b32 v2, v4, 3, s0
	v_mov_b32_e32 v3, s1
	s_mov_b64 s[0:1], 0
	v_readlane_b32 s7, v254, 8
	v_readlane_b32 s9, v254, 10
	s_mov_b32 s11, 0
	v_readlane_b32 s13, v254, 41
	s_movk_i32 s14, 0x600
	s_mov_b32 s27, 0
.LBB0_503:
	v_alignbit_b32 v10, v1, v0, 5
	v_mad_u64_u32 v[6:7], s[4:5], v10, 48, s[8:9]
	v_mov_b32_e32 v8, v7
	v_lshrrev_b32_e32 v11, 5, v1
	v_bfe_u32 v5, v0, 3, 2
	v_mad_u64_u32 v[8:9], s[4:5], v11, 48, v[8:9]
	v_mov_b32_e32 v7, v8
	v_lshlrev_b32_e32 v136, 2, v5
	v_lshl_add_u64 v[6:7], v[6:7], 0, v[136:137]
	global_load_dword v8, v[6:7], off
	global_load_dword v9, v[6:7], off offset:16
	s_nop 0
	global_load_dword v6, v[6:7], off offset:32
	v_lshlrev_b32_e32 v136, 7, v5
	v_lshlrev_b32_e32 v5, 1, v2
	v_and_b32_e32 v26, 0x70, v5
	v_mov_b32_e32 v27, v137
	v_lshrrev_b64 v[18:19], 5, v[0:1]
	v_lshl_add_u64 v[0:1], v[0:1], 0, s[10:11]
	v_lshl_add_u64 v[2:3], v[2:3], 0, s[26:27]
	s_waitcnt vmcnt(0)
	v_max3_f32 v7, v8, v9, v6
	v_sub_f32_e32 v8, v8, v7
	v_sub_f32_e32 v9, v9, v7
	v_mul_f32_e32 v8, 0x3fb8aa3b, v8
	v_mul_f32_e32 v9, 0x3fb8aa3b, v9
	v_sub_f32_e32 v6, v6, v7
	v_exp_f32_e32 v8, v8
	v_exp_f32_e32 v9, v9
	v_mul_f32_e32 v6, 0x3fb8aa3b, v6
	v_exp_f32_e32 v6, v6
	v_add_f32_e32 v7, v8, v9
	v_add_f32_e32 v7, v6, v7
	v_rcp_f32_e32 v7, v7
	s_nop 0
	v_mul_f32_e32 v20, v8, v7
	v_mul_f32_e32 v22, v9, v7
	v_mul_f32_e32 v24, v6, v7
	v_mov_b64_e32 v[6:7], s[6:7]
	v_mad_u64_u32 v[6:7], s[4:5], v10, s14, v[6:7]
	v_mov_b32_e32 v8, v7
	v_mad_u64_u32 v[8:9], s[4:5], v11, s14, v[8:9]
	v_mov_b32_e32 v7, v8
	v_lshl_add_u64 v[6:7], v[6:7], 0, v[136:137]
	v_lshl_add_u64 v[14:15], v[6:7], 0, v[26:27]
	global_load_dwordx4 v[6:9], v[14:15], off
	global_load_dwordx4 v[10:13], v[14:15], off offset:512
	s_nop 0
	global_load_dwordx4 v[14:17], v[14:15], off offset:1024
	s_mov_b64 s[4:5], s[92:93]
	v_cmp_lt_u64_e32 vcc, s[4:5], v[0:1]
	s_or_b64 s[0:1], vcc, s[0:1]
	s_waitcnt vmcnt(2)
	v_lshlrev_b32_e32 v28, 16, v6
	v_and_b32_e32 v29, 0xffff0000, v6
	v_lshlrev_b32_e32 v6, 16, v7
	v_and_b32_e32 v7, 0xffff0000, v7
	s_waitcnt vmcnt(1)
	v_lshlrev_b32_e32 v30, 16, v10
	v_and_b32_e32 v31, 0xffff0000, v10
	v_pk_fma_f32 v[6:7], v[20:21], v[6:7], 0 op_sel_hi:[0,1,0]
	v_lshlrev_b32_e32 v10, 16, v11
	v_and_b32_e32 v11, 0xffff0000, v11
	v_pk_fma_f32 v[6:7], v[22:23], v[10:11], v[6:7] op_sel_hi:[0,1,1]
	s_waitcnt vmcnt(0)
	v_lshlrev_b32_e32 v10, 16, v15
	v_and_b32_e32 v11, 0xffff0000, v15
	v_pk_fma_f32 v[28:29], v[20:21], v[28:29], 0 op_sel_hi:[0,1,0]
	v_pk_fma_f32 v[10:11], v[24:25], v[10:11], v[6:7] op_sel_hi:[0,1,1]
	v_lshlrev_b32_e32 v6, 16, v8
	v_and_b32_e32 v7, 0xffff0000, v8
	v_pk_fma_f32 v[28:29], v[22:23], v[30:31], v[28:29] op_sel_hi:[0,1,1]
	v_lshlrev_b32_e32 v30, 16, v14
	v_and_b32_e32 v31, 0xffff0000, v14
	v_pk_fma_f32 v[6:7], v[20:21], v[6:7], 0 op_sel_hi:[0,1,0]
	v_lshlrev_b32_e32 v14, 16, v12
	v_and_b32_e32 v15, 0xffff0000, v12
	v_pk_fma_f32 v[6:7], v[22:23], v[14:15], v[6:7] op_sel_hi:[0,1,1]
	v_lshlrev_b32_e32 v14, 16, v16
	v_and_b32_e32 v15, 0xffff0000, v16
	v_pk_fma_f32 v[14:15], v[24:25], v[14:15], v[6:7] op_sel_hi:[0,1,1]
	v_lshlrev_b32_e32 v6, 16, v9
	v_and_b32_e32 v7, 0xffff0000, v9
	v_pk_fma_f32 v[6:7], v[20:21], v[6:7], 0 op_sel_hi:[0,1,0]
	v_lshlrev_b32_e32 v8, 16, v13
	v_and_b32_e32 v9, 0xffff0000, v13
	v_pk_fma_f32 v[6:7], v[22:23], v[8:9], v[6:7] op_sel_hi:[0,1,1]
	v_lshlrev_b32_e32 v8, 16, v17
	v_and_b32_e32 v9, 0xffff0000, v17
	v_pk_fma_f32 v[12:13], v[24:25], v[8:9], v[6:7] op_sel_hi:[0,1,1]
	v_cvt_pk_bf16_f32 v7, v10, v11
	v_lshlrev_b64 v[10:11], 9, v[18:19]
	v_lshl_add_u64 v[10:11], s[12:13], 0, v[10:11]
	v_pk_fma_f32 v[28:29], v[24:25], v[30:31], v[28:29] op_sel_hi:[0,1,1]
	v_lshl_add_u64 v[10:11], v[10:11], 0, v[136:137]
	v_cvt_pk_bf16_f32 v6, v28, v29
	v_cvt_pk_bf16_f32 v8, v14, v15
	v_cvt_pk_bf16_f32 v9, v12, v13
	v_lshl_add_u64 v[10:11], v[10:11], 0, v[26:27]
	global_store_dwordx4 v[10:11], v[6:9], off
	s_andn2_b64 exec, exec, s[0:1]
	s_cbranch_execnz .LBB0_503
	s_or_b64 exec, exec, s[0:1]
.LBB0_505:
	v_mov_b32_e32 v0, v154
	v_readlane_b32 s4, v253, 0
	v_readfirstlane_b32 s1, v0
	s_lshl_b32 s0, s4, 1
	s_ashr_i32 s5, s1, 8
	s_add_i32 s0, s5, s0
	s_ashr_i32 s1, s0, 31
	v_readlane_b32 s6, v253, 0
	s_and_b32 s7, s6, 7
	s_lshl_b32 s7, s7, 3
	s_bfe_u32 s8, s6, 0x30003
	s_or_b32 s7, s7, s8
	s_lshr_b32 s8, s6, 6
	s_lshl_b32 s8, s8, 1
	s_and_b32 s9, s0, 1
	s_or_b32 s8, s8, s9
	s_lshl_b32 s0, s7, 7
	s_or_b32 s0, s0, s8
	s_mov_b32 s1, 0
	s_lshl_b32 s92, s7, 15
	s_add_u32 s92, s92, 0x7fff
	s_mov_b32 s93, 0
	s_lshl_b64 s[0:1], s[0:1], 8
	v_mov_b64_e32 v[0:1], 0x1fffff
	v_cmp_gt_u64_e32 vcc, s[0:1], v[0:1]
	s_cbranch_vccnz .LBB0_509
	v_or_b32_e32 v0, s0, v4
	v_readlane_b32 s0, v254, 57
	v_mov_b32_e32 v1, s1
	s_lshl_b32 s0, s0, 7
	s_mov_b32 s1, s52
	v_readlane_b32 s36, v253, 27
	s_lshl_b64 s[0:1], s[0:1], 2
	v_readlane_b32 s48, v253, 39
	v_readlane_b32 s49, v253, 40
	s_add_u32 s0, s48, s0
	s_addc_u32 s1, s49, s1
	s_lshl_b32 s4, s4, 9
	s_lshl_b32 s5, s5, 8
	s_add_i32 s4, s4, s5
	v_mov_b32_e32 v2, v0
	v_readlane_b32 s10, v254, 21
	v_readlane_b32 s12, v254, 34
	s_movk_i32 s14, 0x800
	v_readlane_b32 s26, v254, 42
	v_lshlrev_b32_e32 v6, 3, v2
	s_mov_b64 s[4:5], 0
	v_readlane_b32 s11, v254, 22
	v_readlane_b32 s13, v254, 35
	s_mov_b32 s15, 0
	v_readlane_b32 s27, v254, 43
	s_movk_i32 s23, 0x4000
	s_movk_i32 s36, 0x1800
	v_readlane_b32 s37, v253, 28
	v_readlane_b32 s38, v253, 29
	v_readlane_b32 s39, v253, 30
	v_readlane_b32 s40, v253, 31
	v_readlane_b32 s41, v253, 32
	v_readlane_b32 s42, v253, 33
	v_readlane_b32 s43, v253, 34
	v_readlane_b32 s44, v253, 35
	v_readlane_b32 s45, v253, 36
	v_readlane_b32 s46, v253, 37
	v_readlane_b32 s47, v253, 38
	v_readlane_b32 s50, v253, 41
	v_readlane_b32 s51, v253, 42
.LBB0_507:
	v_lshrrev_b64 v[2:3], 7, v[0:1]
	v_and_b32_e32 v7, 0x3f8, v6
	v_alignbit_b32 v8, v1, v0, 7
	v_mov_b64_e32 v[4:5], s[26:27]
	v_lshlrev_b64 v[20:21], 11, v[2:3]
	v_lshlrev_b32_e32 v136, 1, v7
	v_mad_u64_u32 v[8:9], s[8:9], v8, s36, v[4:5]
	v_lshl_add_u64 v[2:3], s[12:13], 0, v[20:21]
	v_lshrrev_b32_e32 v10, 7, v1
	v_and_b32_e32 v11, 0x78, v6
	v_lshl_add_u64 v[0:1], v[0:1], 0, s[14:15]
	s_mov_b64 s[6:7], s[92:93]
	v_mov_b32_e32 v4, v9
	v_lshl_add_u64 v[2:3], v[2:3], 0, v[136:137]
	v_lshlrev_b32_e32 v7, 2, v11
	v_cmp_lt_u64_e32 vcc, s[6:7], v[0:1]
	v_mad_u64_u32 v[10:11], s[6:7], v10, s36, v[4:5]
	global_load_dwordx4 v[2:5], v[2:3], off
	v_mov_b32_e32 v9, v10
	v_lshl_add_u64 v[8:9], v[8:9], 0, v[136:137]
	global_load_dwordx4 v[8:11], v[8:9], off
	s_nop 0
	global_load_dwordx4 v[12:15], v7, s[0:1] offset:16
	global_load_dwordx4 v[16:19], v7, s[0:1]
	v_lshl_add_u64 v[20:21], s[10:11], 0, v[20:21]
	v_add_u32_e32 v6, s23, v6
	s_or_b64 s[4:5], vcc, s[4:5]
	v_lshl_add_u64 v[20:21], v[20:21], 0, v[136:137]
	s_waitcnt vmcnt(0)
	v_lshlrev_b32_e32 v26, 16, v2
	v_and_b32_e32 v27, 0xffff0000, v2
	v_lshlrev_b32_e32 v22, 16, v5
	v_and_b32_e32 v23, 0xffff0000, v5
	v_lshlrev_b32_e32 v24, 16, v4
	v_and_b32_e32 v25, 0xffff0000, v4
	v_lshlrev_b32_e32 v4, 16, v3
	v_and_b32_e32 v5, 0xffff0000, v3
	v_pk_mul_f32 v[32:33], v[26:27], v[26:27]
	v_pk_mul_f32 v[30:31], v[4:5], v[4:5]
	v_lshlrev_b32_e32 v34, 16, v11
	v_and_b32_e32 v35, 0xffff0000, v11
	v_lshlrev_b32_e32 v36, 16, v10
	v_and_b32_e32 v11, 0xffff0000, v9
	v_add_f32_e32 v7, v32, v33
	v_and_b32_e32 v37, 0xffff0000, v10
	v_lshlrev_b32_e32 v10, 16, v9
	v_lshlrev_b32_e32 v38, 16, v8
	v_and_b32_e32 v39, 0xffff0000, v8
	v_mul_f32_e32 v8, 0xbfb8aa3b, v36
	v_mul_f32_e32 v33, 0xbfb8aa3b, v11
	v_add_f32_e32 v7, v30, v7
	v_pk_mul_f32 v[28:29], v[24:25], v[24:25]
	v_mul_f32_e32 v9, 0xbfb8aa3b, v37
	v_mul_f32_e32 v32, 0xbfb8aa3b, v10
	v_mul_f32_e32 v40, 0xbfb8aa3b, v38
	v_mul_f32_e32 v41, 0xbfb8aa3b, v39
	v_mul_f32_e32 v30, 0xbfb8aa3b, v34
	v_mul_f32_e32 v42, 0xbfb8aa3b, v35
	v_exp_f32_e32 v8, v8
	v_exp_f32_e32 v33, v33
	v_add_f32_e32 v7, v31, v7
	v_exp_f32_e32 v9, v9
	v_exp_f32_e32 v32, v32
	v_exp_f32_e32 v40, v40
	v_exp_f32_e32 v41, v41
	v_exp_f32_e32 v30, v30
	v_exp_f32_e32 v31, v42
	v_add_f32_e32 v7, v28, v7
	v_pk_mul_f32 v[2:3], v[22:23], v[22:23]
	v_add_f32_e32 v7, v29, v7
	v_add_f32_e32 v2, v2, v7
	v_add_f32_e32 v7, 1.0, v8
	v_add_f32_e32 v28, 1.0, v33
	v_add_f32_e32 v33, v3, v2
	v_add_f32_e32 v8, 1.0, v9
	v_add_f32_e32 v9, 1.0, v32
	v_add_f32_e32 v29, 1.0, v40
	v_add_f32_e32 v32, 1.0, v41
	v_add_f32_e32 v30, 1.0, v30
	v_add_f32_e32 v31, 1.0, v31
	v_rcp_f32_e32 v2, v7
	v_add_f32_dpp v7, v33, v33 quad_perm:[1,0,3,2] row_mask:0xf bank_mask:0xf bound_ctrl:1
	v_rcp_f32_e32 v3, v8
	v_rcp_f32_e32 v8, v9
	v_rcp_f32_e32 v9, v28
	v_rcp_f32_e32 v28, v29
	v_rcp_f32_e32 v29, v32
	v_rcp_f32_e32 v30, v30
	v_rcp_f32_e32 v31, v31
	v_add_f32_dpp v7, v7, v7 quad_perm:[2,3,0,1] row_mask:0xf bank_mask:0xf bound_ctrl:1
	v_pk_mul_f32 v[8:9], v[8:9], v[10:11]
	v_pk_mul_f32 v[10:11], v[28:29], v[38:39]
	v_add_f32_dpp v7, v7, v7 row_half_mirror row_mask:0xf bank_mask:0xf bound_ctrl:1
	v_pk_mul_f32 v[28:29], v[30:31], v[34:35]
	v_pk_mul_f32 v[2:3], v[2:3], v[36:37]
	v_add_f32_dpp v7, v7, v7 row_mirror row_mask:0xf bank_mask:0xf bound_ctrl:1
	v_fmamk_f32 v7, v7, 0x3c000000, v155
	v_rsq_f32_e32 v30, v7
	s_nop 0
	v_pk_mul_f32 v[26:27], v[30:31], v[26:27] op_sel_hi:[0,1]
	v_pk_mul_f32 v[4:5], v[30:31], v[4:5] op_sel_hi:[0,1]
	v_pk_mul_f32 v[24:25], v[30:31], v[24:25] op_sel_hi:[0,1]
	v_pk_mul_f32 v[22:23], v[30:31], v[22:23] op_sel_hi:[0,1]
	v_pk_mul_f32 v[16:17], v[16:17], v[26:27]
	v_pk_mul_f32 v[4:5], v[18:19], v[4:5]
	v_pk_mul_f32 v[12:13], v[12:13], v[24:25]
	v_pk_mul_f32 v[14:15], v[14:15], v[22:23]
	v_pk_mul_f32 v[10:11], v[10:11], v[16:17]
	v_pk_mul_f32 v[4:5], v[8:9], v[4:5]
	v_pk_mul_f32 v[8:9], v[2:3], v[12:13]
	v_pk_mul_f32 v[12:13], v[28:29], v[14:15]
	v_cvt_pk_bf16_f32 v2, v10, v11
	v_cvt_pk_bf16_f32 v3, v4, v5
	v_cvt_pk_bf16_f32 v4, v8, v9
	v_cvt_pk_bf16_f32 v5, v12, v13
	global_store_dwordx4 v[20:21], v[2:5], off
	s_andn2_b64 exec, exec, s[4:5]
	s_cbranch_execnz .LBB0_507
	s_or_b64 exec, exec, s[4:5]
